# grid barrier: agent-scope L1 invalidate issued when the workgroup starts waiting (with the leader's L2 write-back / before the first poll) instead of after the release
# speedup vs baseline: 1.0112x; 1.0112x over previous
.LBB0_47:
	s_or_b64 exec, exec, s[6:7]
	v_cvt_f32_u32_e32 v6, v4
	s_waitcnt vmcnt(0)
	v_readfirstlane_b32 s4, v5
	v_sub_u32_e32 v5, 0, v4
	v_rcp_iflag_f32_e32 v6, v6
	v_add_u32_e32 v7, s4, v3
	v_mul_f32_e32 v6, 0x4f7ffffe, v6
	v_cvt_u32_f32_e32 v6, v6
	v_mul_lo_u32 v3, v5, v6
	v_mul_hi_u32 v3, v6, v3
	v_add_u32_e32 v3, v6, v3
	v_mul_hi_u32 v3, v7, v3
	v_mul_lo_u32 v5, v3, v4
	v_sub_u32_e32 v5, v7, v5
	v_add_u32_e32 v6, 1, v3
	v_cmp_ge_u32_e32 vcc, v5, v4
	s_nop 1
	v_cndmask_b32_e32 v3, v3, v6, vcc
	v_sub_u32_e32 v6, v5, v4
	v_cndmask_b32_e32 v5, v5, v6, vcc
	v_add_u32_e32 v6, 1, v3
	v_cmp_ge_u32_e32 vcc, v5, v4
	v_add_u32_e32 v5, 1, v7
	s_nop 0
	v_cndmask_b32_e32 v3, v3, v6, vcc
	v_mul_lo_u32 v6, v4, v3
	v_add_u32_e32 v4, v6, v4
	v_cmp_ne_u32_e32 vcc, v5, v4
	s_and_saveexec_b64 s[4:5], vcc
	s_xor_b64 s[4:5], exec, s[4:5]
	s_cbranch_execz .LBB0_61
	s_waitcnt lgkmcnt(0)
	v_mov_b32_e32 v2, 0x2000
	buffer_inv sc1
	global_load_dword v2, v2, s[2:3] offset:1024 sc1
	s_add_u32 s12, s2, 0x2400
	s_addc_u32 s13, s3, 0
	s_waitcnt vmcnt(0)
	v_cmp_eq_u32_e32 vcc, v2, v3
	s_and_saveexec_b64 s[6:7], vcc
	s_cbranch_execz .LBB0_60
	s_add_u32 s8, s82, 0x4200
	s_addc_u32 s9, s83, 0
	s_mov_b32 s24, 1
	s_mov_b64 s[14:15], 0
	v_mov_b32_e32 v2, 0
	s_branch .LBB0_51

.LBB0_60:
	s_or_b64 exec, exec, s[6:7]
	s_waitcnt vmcnt(0)
	s_waitcnt vmcnt(0)
.LBB0_61:
	s_andn2_saveexec_b64 s[4:5], s[4:5]
	s_cbranch_execz .LBB0_81
	s_mov_b64 s[4:5], exec
	buffer_wbl2 sc1
	buffer_inv sc1
	s_waitcnt lgkmcnt(0)
	s_waitcnt vmcnt(0)
	v_mbcnt_lo_u32_b32 v3, s4, 0
	v_mbcnt_hi_u32_b32 v3, s5, v3
	v_cmp_eq_u32_e32 vcc, 0, v3
	s_and_saveexec_b64 s[6:7], vcc
	s_cbranch_execz .LBB0_64
	s_bcnt1_i32_b64 s4, s[4:5]
	v_mov_b32_e32 v4, 0x7000
	v_mov_b32_e32 v5, s4
	global_atomic_add v4, v4, v5, s[82:83] offset:1024 sc0

.LBB0_78:
	s_or_b64 exec, exec, s[4:5]
	s_mov_b64 s[4:5], exec
	v_mbcnt_lo_u32_b32 v2, s4, 0
	v_mbcnt_hi_u32_b32 v2, s5, v2
	v_cmp_eq_u32_e32 vcc, 0, v2
	s_waitcnt vmcnt(0)
	s_and_saveexec_b64 s[6:7], vcc
	s_cbranch_execz .LBB0_80
	s_bcnt1_i32_b64 s4, s[4:5]
	v_mov_b32_e32 v2, 0x2000
	v_mov_b32_e32 v3, s4
	global_atomic_add v2, v3, s[2:3] offset:1024

.LBB0_189:
	s_or_b64 exec, exec, s[6:7]
	v_cvt_f32_u32_e32 v6, v4
	s_waitcnt vmcnt(0)
	v_readfirstlane_b32 s4, v5
	v_sub_u32_e32 v5, 0, v4
	v_rcp_iflag_f32_e32 v6, v6
	v_add_u32_e32 v7, s4, v3
	v_mul_f32_e32 v6, 0x4f7ffffe, v6
	v_cvt_u32_f32_e32 v6, v6
	v_mul_lo_u32 v3, v5, v6
	v_mul_hi_u32 v3, v6, v3
	v_add_u32_e32 v3, v6, v3
	v_mul_hi_u32 v3, v7, v3
	v_mul_lo_u32 v5, v3, v4
	v_sub_u32_e32 v5, v7, v5
	v_add_u32_e32 v6, 1, v3
	v_cmp_ge_u32_e32 vcc, v5, v4
	s_nop 1
	v_cndmask_b32_e32 v3, v3, v6, vcc
	v_sub_u32_e32 v6, v5, v4
	v_cndmask_b32_e32 v5, v5, v6, vcc
	v_add_u32_e32 v6, 1, v3
	v_cmp_ge_u32_e32 vcc, v5, v4
	v_add_u32_e32 v5, 1, v7
	s_nop 0
	v_cndmask_b32_e32 v3, v3, v6, vcc
	v_mul_lo_u32 v6, v4, v3
	v_add_u32_e32 v4, v6, v4
	v_cmp_ne_u32_e32 vcc, v5, v4
	s_and_saveexec_b64 s[4:5], vcc
	s_xor_b64 s[4:5], exec, s[4:5]
	s_cbranch_execz .LBB0_204
	s_waitcnt lgkmcnt(0)
	v_mov_b32_e32 v2, 0x2000
	buffer_inv sc1
	global_load_dword v2, v2, s[2:3] offset:1024 sc1
	s_add_u32 s10, s2, 0x2400
	s_addc_u32 s11, s3, 0
	s_waitcnt vmcnt(0)
	v_cmp_eq_u32_e32 vcc, v2, v3
	s_and_saveexec_b64 s[6:7], vcc
	s_cbranch_execz .LBB0_203
	s_add_u32 s8, s82, 0x4200
	s_addc_u32 s9, s83, 0
	s_mov_b32 s22, 1
	s_mov_b64 s[12:13], 0
	v_mov_b32_e32 v2, 0
	s_branch .LBB0_193

.LBB0_477:
	s_or_b64 exec, exec, s[8:9]
	v_cvt_f32_u32_e32 v6, v4
	s_waitcnt vmcnt(0)
	v_readfirstlane_b32 s6, v5
	v_sub_u32_e32 v5, 0, v4
	v_rcp_iflag_f32_e32 v6, v6
	v_add_u32_e32 v7, s6, v3
	v_mul_f32_e32 v6, 0x4f7ffffe, v6
	v_cvt_u32_f32_e32 v6, v6
	v_mul_lo_u32 v3, v5, v6
	v_mul_hi_u32 v3, v6, v3
	v_add_u32_e32 v3, v6, v3
	v_mul_hi_u32 v3, v7, v3
	v_mul_lo_u32 v5, v3, v4
	v_sub_u32_e32 v5, v7, v5
	v_add_u32_e32 v6, 1, v3
	v_cmp_ge_u32_e32 vcc, v5, v4
	s_nop 1
	v_cndmask_b32_e32 v3, v3, v6, vcc
	v_sub_u32_e32 v6, v5, v4
	v_cndmask_b32_e32 v5, v5, v6, vcc
	v_add_u32_e32 v6, 1, v3
	v_cmp_ge_u32_e32 vcc, v5, v4
	v_add_u32_e32 v5, 1, v7
	s_nop 0
	v_cndmask_b32_e32 v3, v3, v6, vcc
	v_mul_lo_u32 v6, v4, v3
	v_add_u32_e32 v4, v6, v4
	v_cmp_ne_u32_e32 vcc, v5, v4
	s_and_saveexec_b64 s[6:7], vcc
	s_xor_b64 s[6:7], exec, s[6:7]
	s_cbranch_execz .LBB0_491
	s_waitcnt lgkmcnt(0)
	v_mov_b32_e32 v2, 0x2000
	buffer_inv sc1
	global_load_dword v2, v2, s[2:3] offset:1024 sc1
	s_add_u32 s14, s2, 0x2400
	s_addc_u32 s15, s3, 0
	s_waitcnt vmcnt(0)
	v_cmp_eq_u32_e32 vcc, v2, v3
	s_and_saveexec_b64 s[8:9], vcc
	s_cbranch_execz .LBB0_490
	s_add_u32 s12, s82, 0x4200
	s_addc_u32 s13, s83, 0
	s_mov_b32 s26, 1
	s_mov_b64 s[16:17], 0
	v_mov_b32_e32 v2, 0
	s_branch .LBB0_481

.LBB0_490:
	s_or_b64 exec, exec, s[8:9]
	s_waitcnt vmcnt(0)
	s_waitcnt vmcnt(0)
.LBB0_491:
	s_andn2_saveexec_b64 s[6:7], s[6:7]
	s_cbranch_execz .LBB0_511
	s_mov_b64 s[6:7], exec
	buffer_wbl2 sc1
	buffer_inv sc1
	s_waitcnt lgkmcnt(0)
	s_waitcnt vmcnt(0)
	v_mbcnt_lo_u32_b32 v3, s6, 0
	v_mbcnt_hi_u32_b32 v3, s7, v3
	v_cmp_eq_u32_e32 vcc, 0, v3
	s_and_saveexec_b64 s[8:9], vcc
	s_cbranch_execz .LBB0_494
	s_bcnt1_i32_b64 s6, s[6:7]
	v_mov_b32_e32 v4, 0x7000
	v_mov_b32_e32 v5, s6
	global_atomic_add v4, v4, v5, s[82:83] offset:1024 sc0

.LBB0_508:
	s_or_b64 exec, exec, s[6:7]
	s_mov_b64 s[6:7], exec
	v_mbcnt_lo_u32_b32 v2, s6, 0
	v_mbcnt_hi_u32_b32 v2, s7, v2
	v_cmp_eq_u32_e32 vcc, 0, v2
	s_waitcnt vmcnt(0)
	s_and_saveexec_b64 s[8:9], vcc
	s_cbranch_execz .LBB0_510
	s_bcnt1_i32_b64 s6, s[6:7]
	v_mov_b32_e32 v2, 0x2000
	v_mov_b32_e32 v3, s6
	global_atomic_add v2, v3, s[2:3] offset:1024
